# mLSTM LDS row images (Q, K rows, C state): pairwise chunk swizzle in rows 4..11 mod 16 removes the 2-way ds_read_b128 bank conflicts of S2
# speedup vs baseline: 1.0023x; 1.0023x over previous
; #define LAS __attribute__((address_space(3)))
; __device__ __forceinline__ void mlstm_unit(KArg P, int L, int b, int h, int vs, LAS unsigned char* lds) {
;     ...
;     auto stage_qk = [&]() {
; #pragma unroll
;         for (int r = 0; r < 8; ++r) *(LAS v4u*)(lds + (isk ? ML_KS : ML_QS) + (w * 8 + r) * 528 + (cgp & 31) * 16) = raw[r];
;     };
;     auto stage_kt_v = [&](LAS float* gbn) {
;         if (isk) {
; #pragma unroll
;             for (int e = 0; e < 8; ++e) {
;                 v4u t;
;     ...
;                 if (e & 1) { t.x = (PKW(0) >> 16) | (PKW(1) & 0xffff0000u); t.y = (PKW(2) >> 16) | (PKW(3) & 0xffff0000u); t.z = (PKW(4) >> 16) | (PKW(5) & 0xffff0000u); t.w = (PKW(6) >> 16) | (PKW(7) & 0xffff0000u); }
;                 else { t.x = (PKW(0) & 0xffffu) | (PKW(1) << 16); t.y = (PKW(2) & 0xffffu) | (PKW(3) << 16); t.z = (PKW(4) & 0xffffu) | (PKW(5) << 16); t.w = (PKW(6) & 0xffffu) | (PKW(7) << 16); }
;     ...
;                 *(LAS v4u*)(lds + ML_KT + ((cgp & 31) * 8 + e) * 144 + ((w ^ (((cgp & 31) >> 1) & 7)) * 16)) = t; }
;         }
.LBB0_513:
	v_cmp_gt_u32_e32 vcc, 32, v2
	v_mov_b32_e32 v0, 0x8400
	s_mul_i32 s4, s40, 0x1080
	v_cndmask_b32_e64 v0, v0, 0, vcc
	s_add_i32 s4, s4, 0
	v_lshlrev_b32_e32 v44, 4, v2
	v_add_u32_e32 v0, s4, v0
	v_and_b32_e32 v44, 0x1f0, v44
	v_add_u32_e32 v98, v0, v44
	v_and_b32_e32 v243, 1, v2
	s_bitcmp1_b32 s40, 0
	v_lshlrev_b32_e32 v243, 5, v243
	s_cselect_b64 vcc, -1, 0
	v_sub_u32_e32 v243, 16, v243
	s_nop 0
	v_cndmask_b32_e32 v244, 0, v243, vcc
	v_cndmask_b32_e32 v245, v243, v1, vcc
	v_add_u32_e32 v244, v98, v244
	v_add_u32_e32 v245, v98, v245
	v_lshrrev_b32_e32 v0, 1, v42
	v_cmp_lt_u32_e64 s[10:11], 31, v2
	v_bitop3_b32 v0, s40, v0, 7 bitop3:0x78
	s_waitcnt vmcnt(0) lgkmcnt(0)
	s_barrier
	ds_write_b128 v244, v[4:7]
	ds_write_b128 v244, v[8:11] offset:528
	ds_write_b128 v244, v[12:15] offset:1056
	ds_write_b128 v244, v[16:19] offset:1584
	ds_write_b128 v245, v[20:23] offset:2112
	ds_write_b128 v245, v[24:27] offset:2640
	ds_write_b128 v245, v[28:31] offset:3168
	ds_write_b128 v245, v[32:35] offset:3696
	s_and_saveexec_b64 s[14:15], s[10:11]
	s_cbranch_execz .LBB0_515
	v_and_b32_e32 v44, 0xffff, v4
	v_and_b32_e32 v45, 0xffff, v12
	v_and_b32_e32 v46, 0xffff, v20
	v_and_b32_e32 v47, 0xffff, v28
	v_mul_u32_u24_e32 v48, 0x90, v43
	v_lshlrev_b32_e32 v49, 4, v0
	v_readlane_b32 s4, v254, 19
	v_lshl_or_b32 v44, v8, 16, v44
	v_lshl_or_b32 v45, v16, 16, v45
	v_lshl_or_b32 v46, v24, 16, v46
	v_lshl_or_b32 v47, v32, 16, v47
	v_add3_u32 v50, s4, v48, v49
	ds_write_b128 v50, v[44:47]
	v_lshrrev_b32_e32 v44, 16, v4
	s_mov_b32 s4, 0xffff0000
	v_lshrrev_b32_e32 v45, 16, v12
	v_lshrrev_b32_e32 v46, 16, v20
	v_lshrrev_b32_e32 v47, 16, v28
	v_readlane_b32 s17, v254, 20
	v_and_or_b32 v44, v8, s4, v44
	v_and_or_b32 v45, v16, s4, v45
	v_and_or_b32 v46, v24, s4, v46
	v_and_or_b32 v47, v32, s4, v47
	v_add3_u32 v50, s17, v48, v49
	ds_write_b128 v50, v[44:47]
	v_and_b32_e32 v44, 0xffff, v5
	v_and_b32_e32 v45, 0xffff, v13
	v_and_b32_e32 v46, 0xffff, v21
	v_and_b32_e32 v47, 0xffff, v29
	v_readlane_b32 s17, v254, 21
	v_lshl_or_b32 v44, v9, 16, v44
	v_lshl_or_b32 v45, v17, 16, v45
	v_lshl_or_b32 v46, v25, 16, v46
	v_lshl_or_b32 v47, v33, 16, v47
	v_add3_u32 v50, s17, v48, v49
	ds_write_b128 v50, v[44:47]
	v_lshrrev_b32_e32 v44, 16, v5
	v_lshrrev_b32_e32 v45, 16, v13
	v_lshrrev_b32_e32 v46, 16, v21
	v_lshrrev_b32_e32 v47, 16, v29
	v_readlane_b32 s17, v254, 22
	v_and_or_b32 v44, v9, s4, v44
	v_and_or_b32 v45, v17, s4, v45
	v_and_or_b32 v46, v25, s4, v46
	v_and_or_b32 v47, v33, s4, v47
	v_add3_u32 v50, s17, v48, v49
	ds_write_b128 v50, v[44:47]
	v_and_b32_e32 v44, 0xffff, v6
	v_and_b32_e32 v45, 0xffff, v14
	v_and_b32_e32 v46, 0xffff, v22
	v_and_b32_e32 v47, 0xffff, v30
	v_readlane_b32 s17, v254, 23
	v_lshl_or_b32 v44, v10, 16, v44
	v_lshl_or_b32 v45, v18, 16, v45
	v_lshl_or_b32 v46, v26, 16, v46
	v_lshl_or_b32 v47, v34, 16, v47
	v_add3_u32 v50, s17, v48, v49
	ds_write_b128 v50, v[44:47]
	v_lshrrev_b32_e32 v44, 16, v6
	v_lshrrev_b32_e32 v45, 16, v14
	v_lshrrev_b32_e32 v46, 16, v22
	v_lshrrev_b32_e32 v47, 16, v30
	v_readlane_b32 s17, v254, 24
	v_and_or_b32 v44, v10, s4, v44
	v_and_or_b32 v45, v18, s4, v45
	v_and_or_b32 v46, v26, s4, v46
	v_and_or_b32 v47, v34, s4, v47
	v_add3_u32 v50, s17, v48, v49
	ds_write_b128 v50, v[44:47]
	v_and_b32_e32 v44, 0xffff, v7
	v_and_b32_e32 v45, 0xffff, v15
	v_and_b32_e32 v46, 0xffff, v23
	v_and_b32_e32 v47, 0xffff, v31
	v_readlane_b32 s17, v254, 25
	v_lshl_or_b32 v44, v11, 16, v44
	v_lshl_or_b32 v45, v19, 16, v45
	v_lshl_or_b32 v46, v27, 16, v46
	v_lshl_or_b32 v47, v35, 16, v47
	v_add3_u32 v50, s17, v48, v49
	ds_write_b128 v50, v[44:47]
	v_lshrrev_b32_e32 v44, 16, v7
	v_lshrrev_b32_e32 v45, 16, v15
	v_lshrrev_b32_e32 v46, 16, v23
	v_lshrrev_b32_e32 v47, 16, v31
	v_and_or_b32 v44, v11, s4, v44
	v_and_or_b32 v45, v19, s4, v45
	v_and_or_b32 v46, v27, s4, v46
	v_and_or_b32 v47, v35, s4, v47
	v_readlane_b32 s4, v254, 26
	s_nop 1
	v_add3_u32 v48, s4, v48, v49
	ds_write_b128 v48, v[44:47]

; #define LAS __attribute__((address_space(3)))
; __device__ __forceinline__ void mlstm_unit(KArg P, int L, int b, int h, int vs, LAS unsigned char* lds) {
;     ...
;         {
;             const LAS unsigned char* qp = lds + ML_QS + (ttile * 16 + c) * 528 + g * 16;
;             const LAS unsigned char* k0p = lds + ML_KS + ((par * 2 + 0) * 16 + c) * 528 + g * 16;
;             const LAS unsigned char* k1p = lds + ML_KS + ((par * 2 + 1) * 16 + c) * 528 + g * 16;
;             const LAS unsigned char* cp = lds + ML_CB + (par * 16 + c) * 528 + g * 16;
; #pragma unroll 2
;             for (int kk = 0; kk < 8; ++kk) {
;                 const bf16x8 a = *(const LAS bf16x8*)(qp + kk * 64);
;                 const bf16x8 b0 = *(const LAS bf16x8*)(k0p + kk * 64), b1 = *(const LAS bf16x8*)(k1p + kk * 64), bc = *(const LAS bf16x8*)(cp + kk * 64);
;                 accS0 = MFMA16(a, b0, accS0); accS1 = MFMA16(a, b1, accS1); accI = MFMA16(a, bc, accI);
;                 { const bf16x8 bn = *(const LAS bf16x8*)(lds + ML_NB + kk * 64 + g * 16); accN = MFMA16(a, bn, accN); } }
; #pragma unroll
;             for (int r = 0; r < 4; ++r) { const int t = ttile * 16 + 4 * g + r; const float Mt = GB[FL_MX + t];
;                 const int s0 = (par * 2) * 16 + c, s1 = s0 + 16;
;                 const float w0 = (s0 <= t) ? __expf(GB[FL_A + s0] - Mt) : 0.f, w1 = (s1 <= t) ? __expf(GB[FL_A + s1] - Mt) : 0.f;
;                 *(LAS bf16*)(lds + ML_PS + t * 144 + s0 * 2) = (bf16)(cvt_pk_bf16(accS0[r] * w0, 0.f) & 0xffffu);
;                 *(LAS bf16*)(lds + ML_PS + t * 144 + s1 * 2) = (bf16)(cvt_pk_bf16(accS1[r] * w1, 0.f) & 0xffffu); }
;         }
;         __syncthreads();
;         {
;             f32x4 accP = (f32x4){0.f, 0.f, 0.f, 0.f}, accR = accP;
;             const bf16x8 ones8 = (bf16x8){0x3f80, 0x3f80, 0x3f80, 0x3f80, 0x3f80, 0x3f80, 0x3f80, 0x3f80};
; #pragma unroll
;             for (int ks = 0; ks < 2; ++ks) {
;                 const bf16x8 a = *(const LAS bf16x8*)(lds + ML_PS + (ttile * 16 + c) * 144 + ks * 64 + g * 16);
;                 const bf16x8 bv = *(const LAS bf16x8*)(lds + ML_VT + (par * 16 + c) * 144 + ks * 64 + g * 16);
;                 accP = MFMA16(a, bv, accP); accR = MFMA16(a, ones8, accR); }
; #pragma unroll
;             for (int r = 0; r < 4; ++r) { const int t = ttile * 16 + 4 * g + r; const float wi = GB[FL_WIN + t];
.LBB0_519:
	s_or_b64 exec, exec, s[12:13]
	s_lshl_b32 s41, s16, 5
	v_readlane_b32 s16, v254, 20
	v_lshlrev_b32_e32 v52, 4, v0
	v_readlane_b32 s12, v254, 43
	v_mov_b32_e32 v0, s16
	v_readlane_b32 s16, v254, 21
	v_mad_u32_u24 v53, v43, s86, v0
	v_mov_b32_e32 v41, v1
	v_mov_b32_e32 v0, s16
	v_readlane_b32 s16, v254, 22
	v_readlane_b32 s13, v254, 44
	v_mad_u32_u24 v54, v43, s86, v0
	v_mov_b32_e32 v0, s16
	v_readlane_b32 s16, v254, 23
	v_and_b32_e32 v46, 15, v42
	s_bfe_u32 s4, s35, 0x10006
	v_lshl_add_u64 v[84:85], s[12:13], 0, v[40:41]
	v_bfi_b32 v40, -16, s53, v42
	v_mad_u32_u24 v55, v43, s86, v0
	v_mov_b32_e32 v0, s16
	v_readlane_b32 s16, v254, 24
	v_lshrrev_b32_e32 v45, 4, v2
	v_lshl_or_b32 v108, s4, 5, v46
	s_lshl_b32 s4, s4, 4
	v_mul_lo_u32 v40, v40, s86
	v_readlane_b32 s20, v254, 29
	v_readlane_b32 s17, v254, 27
	v_mad_u32_u24 v56, v43, s86, v0
	v_mov_b32_e32 v0, s16
	v_readlane_b32 s16, v254, 25
	v_and_b32_e32 v107, 48, v42
	v_or_b32_e32 v42, s4, v46
	v_lshlrev_b32_e32 v48, 2, v45
	v_add_u32_e32 v49, s20, v40
	v_mov_b32_e32 v40, s17
	v_readlane_b32 s39, v254, 19
	v_mad_u32_u24 v57, v43, s86, v0
	v_mov_b32_e32 v0, s16
	v_readlane_b32 s16, v254, 26
	v_mul_u32_u24_e32 v47, 0x210, v42
	v_and_or_b32 v86, s53, -16, v48
	v_mad_u32_u24 v42, v42, s86, v40
	v_mov_b32_e32 v40, s39
	v_mad_u32_u24 v58, v43, s86, v0
	v_mov_b32_e32 v0, s16
	v_mad_u32_u24 v51, v43, s86, v40
	v_mad_u32_u24 v43, v43, s86, v0
	v_mul_lo_u32 v0, v86, s86
	v_add_u32_e32 v114, s20, v0
	v_lshl_or_b32 v0, s40, 5, v46
	s_lshl_b32 s38, s40, 1
	v_readlane_b32 s18, v254, 28
	v_mul_lo_u32 v0, v0, s86
	s_andn2_b32 s35, s35, 63
	v_or_b32_e32 v48, 16, v108
	v_add_u32_e32 v112, s17, v44
	v_add_u32_e32 v113, s18, v44
	v_or_b32_e32 v88, 1, v86
	v_or_b32_e32 v90, 2, v86
	v_or_b32_e32 v92, 3, v86
	v_add_u32_e32 v44, s39, v0
	v_bitop3_b32 v0, s38, v45, 6 bitop3:0x6c
	s_add_i32 s64, s35, 0
	v_lshlrev_b32_e32 v110, 1, v48
	v_add_u32_e32 v50, s18, v107
	v_cmp_le_i32_e64 s[18:19], v48, v86
	v_cmp_le_i32_e64 s[22:23], v48, v88
	v_cmp_le_i32_e64 s[26:27], v48, v90
	v_cmp_le_i32_e64 s[30:31], v48, v92
	v_lshlrev_b32_e32 v48, 4, v0
	v_or_b32_e32 v0, 4, v45
	v_lshlrev_b32_e32 v118, 1, v46
	s_add_i32 s35, s64, 0x1bc00
	v_bitop3_b32 v40, s38, v0, 6 bitop3:0x6c
	v_add_u32_e32 v60, s35, v118
	s_or_b32 s35, s38, 1
	v_lshlrev_b32_e32 v59, 4, v40
	v_lshl_or_b32 v40, s35, 4, v46
	v_mul_lo_u32 v40, v40, s86
	s_add_i32 s16, 0, 0x22200
	s_add_i32 s63, s64, 0x22e40
	v_add_u32_e32 v63, s39, v40
	v_bitop3_b32 v40, s35, v45, 7 bitop3:0x6c
	v_bitop3_b32 v0, s35, v0, 7 bitop3:0x6c
	s_add_i32 s35, s64, 0x1bc20
	s_add_i32 s64, s64, 0x22e60
	s_lshl_b32 s34, s34, 2
	s_add_u32 s38, s0, s34
	v_mul_u32_u24_e32 v41, 0x210, v108
	s_addc_u32 s39, s1, 0
	s_add_i32 s34, 0, 0x8400
	v_add3_u32 v120, v41, v107, s34
	s_lshr_b32 s34, s40, 1
	v_lshlrev_b32_e32 v64, 4, v0
	v_lshlrev_b32_e32 v0, 1, v2
	s_mulk_i32 s34, 0x2100
	v_sub_u32_e32 v119, 0, v0
	v_mov_b32_e32 v0, s34
	s_movk_i32 s34, 0x210
	v_mul_u32_u24_e32 v61, 0x90, v46
	v_mul_u32_u24_e32 v62, 0x840, v45
	v_lshlrev_b32_e32 v45, 4, v40
	v_add_u32_e32 v65, s35, v118
	v_mad_u32_u24 v0, v46, s34, v0
	v_mov_b32_e32 v40, 0
	v_lshlrev_b32_e32 v109, 1, v108
	v_cmp_gt_u32_e64 s[12:13], 16, v2
	v_ashrrev_i32_e32 v81, 31, v80
	v_mov_b32_e32 v83, v1
	s_mov_b32 s43, 0
	v_cmp_eq_u32_e64 s[14:15], 0, v2
	v_lshl_add_u32 v111, v80, 2, s16
	v_cmp_le_i32_e64 s[16:17], v108, v86
	v_cmp_le_i32_e64 s[20:21], v108, v88
	v_add_u32_e32 v115, 0x90, v114
	v_cmp_le_i32_e64 s[24:25], v108, v90
	v_add_u32_e32 v116, 0x120, v114
	v_cmp_le_i32_e64 s[28:29], v108, v92
	v_add_u32_e32 v117, 0x1b0, v114
	v_ashrrev_i32_e32 v87, 31, v86
	v_ashrrev_i32_e32 v89, 31, v88
	v_ashrrev_i32_e32 v91, 31, v90
	v_ashrrev_i32_e32 v93, 31, v92
	v_add_u32_e32 v121, 0, v107
	v_add3_u32 v122, v47, v107, 0
	v_add3_u32 v123, v0, v107, 0
	v_add_u32_e32 v124, v49, v107
	v_add_u32_e32 v125, v42, v107
	s_lshl_b32 s40, s41, 1
	s_lshl_b32 s42, s4, 1
	v_lshlrev_b32_e32 v0, 1, v46
	v_add_u32_e32 v126, v44, v48
	v_add_u32_e32 v127, v44, v59
	v_add_u32_e32 v128, v60, v62
	v_add_u32_e32 v129, v63, v45
	v_add_u32_e32 v130, v63, v64
	v_add_u32_e32 v131, v65, v62
	v_lshrrev_b32_e32 v246, 2, v46
	v_lshrrev_b32_e32 v247, 3, v46
	v_and_b32_e32 v248, 16, v107
	v_xor_b32_e32 v246, v246, v247
	v_lshlrev_b32_e32 v248, 1, v248
	v_and_b32_e32 v246, 1, v246
	v_sub_u32_e32 v248, 16, v248
	v_cmp_eq_u32_e32 vcc, 1, v246
	s_nop 1
	v_cndmask_b32_e32 v248, 0, v248, vcc
	v_add_u32_e32 v120, v120, v248
	v_add_u32_e32 v122, v122, v248
	v_add_u32_e32 v123, v123, v248
	v_lshrrev_b32_e32 v246, 4, v107
	v_lshrrev_b32_e32 v247, 5, v107
	v_and_b32_e32 v248, 8, v46
	v_xor_b32_e32 v246, v246, v247
	v_lshlrev_b32_e32 v248, 2, v248
	v_and_b32_e32 v246, 1, v246
	v_sub_u32_e32 v248, 16, v248
	v_cmp_eq_u32_e32 vcc, 1, v246
	s_nop 1
	v_cndmask_b32_e32 v248, 0, v248, vcc
	v_add_u32_e32 v128, v128, v248
	v_add_u32_e32 v131, v131, v248
	v_add_u32_e32 v132, v51, v52
	v_add_u32_e32 v133, v53, v52
	v_add_u32_e32 v134, v54, v52
	v_add_u32_e32 v135, v55, v52
	v_add_u32_e32 v136, v56, v52
	v_add_u32_e32 v137, v57, v52
	v_add_u32_e32 v138, v58, v52
	v_add_u32_e32 v139, v43, v52
	v_add_u32_e32 v140, v50, v61
	v_mov_b32_e32 v41, v40
	v_mov_b32_e32 v42, v40
	v_mov_b32_e32 v43, v40
	v_mov_b32_e32 v52, v40
	v_mov_b32_e32 v53, v40
	v_mov_b32_e32 v54, v40
	v_mov_b32_e32 v55, v40
	v_mov_b32_e32 v48, v40
	v_mov_b32_e32 v49, v40
	v_mov_b32_e32 v50, v40
	v_mov_b32_e32 v51, v40
	v_mov_b32_e32 v60, v40
	v_mov_b32_e32 v61, v40
	v_mov_b32_e32 v62, v40
	v_mov_b32_e32 v63, v40
	v_mov_b32_e32 v56, v40
	v_mov_b32_e32 v57, v40
	v_mov_b32_e32 v58, v40
	v_mov_b32_e32 v59, v40
	v_mov_b32_e32 v44, v40
	v_mov_b32_e32 v45, v40
	v_mov_b32_e32 v46, v40
	v_mov_b32_e32 v47, v40
	s_waitcnt lgkmcnt(0)
	s_barrier
	s_branch .LBB0_522

; #define LAS __attribute__((address_space(3)))
; __device__ __forceinline__ void mlstm_unit(KArg P, int L, int b, int h, int vs, LAS unsigned char* lds) {
;     ...
;     auto stage_qk = [&]() {
; #pragma unroll
;         for (int r = 0; r < 8; ++r) *(LAS v4u*)(lds + (isk ? ML_KS : ML_QS) + (w * 8 + r) * 528 + (cgp & 31) * 16) = raw[r];
;     };
.LBB0_551:
	s_waitcnt vmcnt(11)
	ds_write_b128 v244, v[4:7]
	s_waitcnt vmcnt(10)
	ds_write_b128 v244, v[8:11] offset:528
	s_waitcnt vmcnt(9)
	ds_write_b128 v244, v[12:15] offset:1056
	s_waitcnt vmcnt(8)
	ds_write_b128 v244, v[16:19] offset:1584
	s_waitcnt vmcnt(7)
	ds_write_b128 v245, v[20:23] offset:2112
	s_waitcnt vmcnt(6)
	ds_write_b128 v245, v[24:27] offset:2640
	s_waitcnt vmcnt(5)
	ds_write_b128 v245, v[28:31] offset:3168
	s_waitcnt vmcnt(4)
	ds_write_b128 v245, v[32:35] offset:3696
